# normmod1: shift/scale loads issued before the next-row prefetch, counted vmcnt(8), next-row wait moved to first use
# baseline (speedup 1.0000x reference)
; __device__ __forceinline__ void phase_normmod(const float* src, const float* gain, const float* ada, int shoff, int scoff, bf16_t* dst) {
;     ...
;     for (int m = gw; m < M_; m += NGW) {
;         const int mn = (m + NGW < M_) ? m + NGW : m;
;         const float* ab = ada + (size_t)(m >> 12) * NADA;
;         f32x4 vn[8], sh[8], sc[8];
; #pragma unroll
;         for (int j = 0; j < 8; ++j) { const int col = 4 * (lane + 64 * j); sh[j] = *(const f32x4*)(ab + shoff + col); sc[j] = *(const f32x4*)(ab + scoff + col); vn[j] = ((const f32x4*)(src + (size_t)mn * D_) + lane)[64 * j]; }
;         __builtin_amdgcn_sched_barrier(0);
;         float ss = 0.f;
; #pragma unroll
;         for (int j = 0; j < 8; ++j) ss += (v[j][0] * v[j][0] + v[j][1] * v[j][1]) + (v[j][2] * v[j][2] + v[j][3] * v[j][3]);
;         ss = wave_sum(ss);
;         const float rstd = rsqrtf(ss * (1.0f / D_) + 1e-6f);
.LBB0_129:
	v_add_u32_e32 v211, s80, v128
	v_cmp_gt_i32_e32 vcc, s2, v211
	v_ashrrev_i32_e32 v65, 12, v128
	v_mul_hi_i32_i24_e32 v67, 0x12000, v65
	v_cndmask_b32_e32 v64, v128, v211, vcc
	v_mul_i32_i24_e32 v66, 0x12000, v65
	v_ashrrev_i32_e32 v65, 31, v64
	v_lshl_add_u64 v[92:93], s[70:71], 0, v[66:67]
	v_lshlrev_b64 v[64:65], 13, v[64:65]
	v_lshl_add_u64 v[94:95], v[92:93], 0, s[10:11]
	v_lshl_add_u64 v[84:85], v[158:159], 0, v[64:65]
	v_mov_b32_e32 v163, v157
	v_mov_b32_e32 v165, v157
	v_lshl_add_u64 v[76:77], v[92:93], 0, v[156:157]
	v_lshl_add_u64 v[72:73], v[94:95], 0, v[156:157]
	v_lshl_add_u64 v[74:75], v[94:95], 0, v[162:163]
	v_lshl_add_u64 v[80:81], v[94:95], 0, v[164:165]
	v_mov_b32_e32 v167, v157
	v_mov_b32_e32 v169, v157
	v_add_co_u32_e32 v120, vcc, s6, v84
	v_mov_b32_e32 v171, v157
	global_load_dwordx4 v[64:67], v[76:77], off
	global_load_dwordx4 v[68:71], v[76:77], off offset:1024
	global_load_dwordx4 v[178:181], v[72:73], off
	global_load_dwordx4 v[152:155], v[74:75], off
	s_nop 0
	global_load_dwordx4 v[72:75], v[76:77], off offset:2048
	s_nop 0
	global_load_dwordx4 v[76:79], v[76:77], off offset:3072
	v_lshl_add_u64 v[82:83], v[94:95], 0, v[166:167]
	global_load_dwordx4 v[132:135], v[80:81], off
	global_load_dwordx4 v[128:131], v[82:83], off
	v_lshl_add_u64 v[80:81], v[92:93], 0, v[168:169]
	v_lshl_add_u64 v[86:87], v[94:95], 0, v[168:169]
	v_addc_co_u32_e32 v121, vcc, 0, v85, vcc
	v_lshl_add_u64 v[84:85], v[92:93], 0, v[170:171]
	v_lshl_add_u64 v[88:89], v[94:95], 0, v[170:171]
	v_mov_b32_e32 v173, v157
	global_load_dwordx4 v[80:83], v[80:81], off
	s_nop 0
	global_load_dwordx4 v[136:139], v[86:87], off
	s_nop 0
	global_load_dwordx4 v[84:87], v[84:85], off
	s_nop 0
	global_load_dwordx4 v[140:143], v[88:89], off
	v_lshl_add_u64 v[88:89], v[92:93], 0, v[172:173]
	v_lshl_add_u64 v[122:123], v[94:95], 0, v[172:173]
	v_mov_b32_e32 v175, v157
	global_load_dwordx4 v[88:91], v[88:89], off
	s_nop 0
	global_load_dwordx4 v[144:147], v[122:123], off
	v_lshl_add_u64 v[92:93], v[92:93], 0, v[174:175]
	v_lshl_add_u64 v[122:123], v[94:95], 0, v[174:175]
	global_load_dwordx4 v[92:95], v[92:93], off
	s_nop 0
	global_load_dwordx4 v[148:151], v[122:123], off
	s_nop 0
	global_load_dwordx4 v[100:103], v[120:121], off offset:-4096
	global_load_dwordx4 v[96:99], v[120:121], off offset:-3072
	global_load_dwordx4 v[108:111], v[120:121], off offset:-2048
	global_load_dwordx4 v[104:107], v[120:121], off offset:-1024
	global_load_dwordx4 v[116:119], v[120:121], off
	global_load_dwordx4 v[112:115], v[120:121], off offset:1024
	global_load_dwordx4 v[124:127], v[120:121], off offset:2048
	global_load_dwordx4 v[120:123], v[120:121], off offset:3072
	v_cmp_lt_i32_e32 vcc, s7, v211
	s_waitcnt vmcnt(8)
	v_pk_add_f32 v[176:177], v[180:181], 1.0 op_sel_hi:[1,0]
	v_pk_mul_f32 v[186:187], v[32:33], v[32:33]
	v_pk_mul_f32 v[180:181], v[36:37], v[36:37]
	v_pk_mul_f32 v[190:191], v[34:35], v[34:35]
	v_pk_mul_f32 v[182:183], v[38:39], v[38:39]
	v_pk_mul_f32 v[192:193], v[42:43], v[42:43]
	v_pk_mul_f32 v[184:185], v[40:41], v[40:41]
	v_mov_b32_e32 v214, v186
	v_mov_b32_e32 v215, v180
	v_mov_b32_e32 v180, v187
	v_mov_b32_e32 v186, v190
	v_mov_b32_e32 v187, v182
	v_mov_b32_e32 v182, v191
	v_pk_mov_b32 v[190:191], v[184:185], v[192:193] op_sel:[1,0]
	v_mov_b32_e32 v185, v193
	v_pk_add_f32 v[180:181], v[214:215], v[180:181]
	v_pk_add_f32 v[182:183], v[186:187], v[182:183]
	v_pk_mul_f32 v[194:195], v[58:59], v[58:59]
	v_pk_mul_f32 v[188:189], v[56:57], v[56:57]
	v_mul_f32_e32 v196, v44, v44
	v_mul_f32_e32 v198, v46, v46
	v_pk_add_f32 v[184:185], v[190:191], v[184:185]
	v_pk_add_f32 v[180:181], v[180:181], v[182:183]
	v_pk_mov_b32 v[192:193], v[188:189], v[194:195] op_sel:[1,0]
	v_mov_b32_e32 v189, v195
	v_pk_fma_f32 v[194:195], v[44:45], v[44:45], v[196:197] op_sel_hi:[1,1,0]
	v_pk_fma_f32 v[216:217], v[46:47], v[46:47], v[198:199] op_sel_hi:[1,1,0]
	v_pk_add_f32 v[184:185], v[184:185], v[184:185] op_sel_hi:[0,1]
	v_pk_add_f32 v[180:181], v[180:181], v[180:181] op_sel_hi:[0,1]
	v_mul_f32_e32 v194, v48, v48
	v_mul_f32_e32 v216, v49, v49
	v_mul_f32_e32 v184, v50, v50
	v_mul_f32_e32 v180, v51, v51
	v_pk_add_f32 v[182:183], v[194:195], v[216:217]
	v_pk_add_f32 v[180:181], v[184:185], v[180:181]
	v_mul_f32_e32 v200, v52, v52
	v_mul_f32_e32 v202, v54, v54
	v_pk_add_f32 v[186:187], v[192:193], v[188:189]
	v_pk_add_f32 v[180:181], v[182:183], v[180:181]
	v_pk_fma_f32 v[218:219], v[52:53], v[52:53], v[200:201] op_sel_hi:[1,1,0]
	v_pk_fma_f32 v[220:221], v[54:55], v[54:55], v[202:203] op_sel_hi:[1,1,0]
	v_pk_add_f32 v[186:187], v[186:187], v[186:187] op_sel_hi:[0,1]
	v_pk_add_f32 v[180:181], v[180:181], v[180:181] op_sel_hi:[0,1]
	v_mul_f32_e32 v218, v207, v207
	v_mul_f32_e32 v220, v208, v208
	v_mul_f32_e32 v186, v210, v210
	v_mul_f32_e32 v180, v209, v209
	v_pk_add_f32 v[188:189], v[218:219], v[220:221]
	v_pk_add_f32 v[180:181], v[186:187], v[180:181]
	v_pk_add_f32 v[212:213], v[128:129], 1.0 op_sel_hi:[1,0]
	v_pk_add_f32 v[180:181], v[188:189], v[180:181]
	s_or_b64 s[8:9], vcc, s[8:9]
	v_add_f32_e32 v129, v180, v181
	ds_bpermute_b32 v163, v197, v129
	v_pk_add_f32 v[178:179], v[178:179], 1.0 op_sel_hi:[1,0]
	v_pk_add_f32 v[154:155], v[154:155], 1.0 op_sel_hi:[1,0]
	v_pk_add_f32 v[152:153], v[152:153], 1.0 op_sel_hi:[1,0]
	v_pk_add_f32 v[134:135], v[134:135], 1.0 op_sel_hi:[1,0]
	s_waitcnt lgkmcnt(0)
	v_add_f32_e32 v129, v129, v163
	ds_bpermute_b32 v163, v199, v129
	v_pk_add_f32 v[132:133], v[132:133], 1.0 op_sel_hi:[1,0]
	v_pk_add_f32 v[130:131], v[130:131], 1.0 op_sel_hi:[1,0]
	v_pk_add_f32 v[138:139], v[138:139], 1.0 op_sel_hi:[1,0]
	v_pk_add_f32 v[136:137], v[136:137], 1.0 op_sel_hi:[1,0]
	s_waitcnt lgkmcnt(0)
; __device__ __forceinline__ unsigned cvt_pk_bf16(float lo, float hi) { f32x2v v = {lo, hi}; bf16x2_t r = __builtin_convertvector(v, bf16x2_t); return __builtin_bit_cast(unsigned, r); }
; __device__ __forceinline__ void phase_normmod(const float* src, const float* gain, const float* ada, int shoff, int scoff, bf16_t* dst) {
;     ...
;         ss = wave_sum(ss);
;         const float rstd = rsqrtf(ss * (1.0f / D_) + 1e-6f);
; #pragma unroll
;         for (int j = 0; j < 8; ++j) { const int col = 4 * (lane + 64 * j);
;             const f32x4 y = v[j] * rstd * g[j] * (sc[j] + 1.0f) + sh[j];
;             u32x2 w; w.x = cvt_pk_bf16(y[0], y[1]); w.y = cvt_pk_bf16(y[2], y[3]);
;             *(u32x2*)(dst + (size_t)m * D_ + col) = w; }
; #pragma unroll
;         for (int j = 0; j < 8; ++j) v[j] = vn[j];
	v_add_f32_e32 v129, v129, v163
	ds_bpermute_b32 v163, v201, v129
	v_pk_add_f32 v[142:143], v[142:143], 1.0 op_sel_hi:[1,0]
	v_pk_add_f32 v[140:141], v[140:141], 1.0 op_sel_hi:[1,0]
	v_pk_add_f32 v[146:147], v[146:147], 1.0 op_sel_hi:[1,0]
	v_pk_add_f32 v[144:145], v[144:145], 1.0 op_sel_hi:[1,0]
	s_waitcnt lgkmcnt(0)
	v_add_f32_e32 v129, v129, v163
	ds_bpermute_b32 v163, v203, v129
	v_pk_add_f32 v[150:151], v[150:151], 1.0 op_sel_hi:[1,0]
	v_pk_add_f32 v[148:149], v[148:149], 1.0 op_sel_hi:[1,0]
	s_waitcnt lgkmcnt(0)
	v_add_f32_e32 v129, v129, v163
	ds_bpermute_b32 v163, v204, v129
	v_mov_b32_e32 v128, v211
	s_waitcnt lgkmcnt(0)
	v_add_f32_e32 v129, v129, v163
	ds_bpermute_b32 v163, v205, v129
	s_waitcnt lgkmcnt(0)
	v_add_f32_e32 v129, v129, v163
	v_fmamk_f32 v129, v129, 0x3a000000, v206
	v_mul_f32_e32 v163, 0x4b800000, v129
	v_cmp_gt_f32_e32 vcc, s12, v129
	s_nop 1
	v_cndmask_b32_e32 v129, v129, v163, vcc
	v_rsq_f32_e32 v129, v129
	s_nop 0
	v_mul_f32_e32 v163, 0x45800000, v129
	v_cndmask_b32_e32 v180, v129, v163, vcc
	v_pk_mul_f32 v[182:183], v[34:35], v[180:181] op_sel_hi:[1,0]
	v_pk_mul_f32 v[184:185], v[32:33], v[180:181] op_sel_hi:[1,0]
	v_pk_mul_f32 v[186:187], v[38:39], v[180:181] op_sel_hi:[1,0]
	v_pk_mul_f32 v[188:189], v[36:37], v[180:181] op_sel_hi:[1,0]
	v_pk_mul_f32 v[190:191], v[42:43], v[180:181] op_sel_hi:[1,0]
	v_pk_mul_f32 v[192:193], v[40:41], v[180:181] op_sel_hi:[1,0]
	v_pk_mul_f32 v[194:195], v[46:47], v[180:181] op_sel_hi:[1,0]
	v_pk_mul_f32 v[214:215], v[44:45], v[180:181] op_sel_hi:[1,0]
	v_pk_mul_f32 v[216:217], v[50:51], v[180:181] op_sel_hi:[1,0]
	v_pk_mul_f32 v[218:219], v[48:49], v[180:181] op_sel_hi:[1,0]
	v_pk_mul_f32 v[220:221], v[58:59], v[180:181] op_sel_hi:[1,0]
	v_pk_mul_f32 v[222:223], v[56:57], v[180:181] op_sel_hi:[1,0]
	v_pk_mul_f32 v[224:225], v[54:55], v[180:181] op_sel_hi:[1,0]
	v_pk_mul_f32 v[226:227], v[52:53], v[180:181] op_sel_hi:[1,0]
	v_pk_mul_f32 v[228:229], v[62:63], v[180:181] op_sel_hi:[1,0]
	v_pk_mul_f32 v[180:181], v[60:61], v[180:181] op_sel_hi:[1,0]
	s_waitcnt vmcnt(0)
	v_mov_b32_e32 v207, v120
	v_mov_b32_e32 v208, v121
	v_mov_b32_e32 v210, v122
	v_mov_b32_e32 v209, v123
	v_mov_b32_e32 v36, v96
	v_mov_b32_e32 v37, v97
	v_mov_b32_e32 v38, v98
	v_mov_b32_e32 v39, v99
	v_mov_b64_e32 v[60:61], v[120:121]
	v_pk_mul_f32 v[96:97], v[2:3], v[182:183]
	v_pk_mul_f32 v[98:99], v[0:1], v[184:185]
	v_mov_b32_e32 v32, v100
	v_mov_b32_e32 v33, v101
	v_mov_b32_e32 v34, v102
	v_mov_b32_e32 v35, v103
	v_mov_b32_e32 v40, v108
	v_mov_b32_e32 v41, v109
	v_mov_b32_e32 v42, v110
	v_mov_b32_e32 v43, v111
	v_mov_b32_e32 v44, v104
	v_mov_b32_e32 v45, v105
	v_mov_b32_e32 v46, v106
	v_mov_b32_e32 v47, v107
	v_mov_b32_e32 v48, v116
	v_mov_b32_e32 v49, v117
	v_mov_b32_e32 v50, v118
	v_mov_b32_e32 v51, v119
	v_mov_b32_e32 v56, v112
	v_mov_b32_e32 v57, v113
	v_mov_b32_e32 v58, v114
	v_mov_b32_e32 v59, v115
	v_mov_b32_e32 v52, v124
	v_mov_b32_e32 v53, v125
	v_mov_b32_e32 v54, v126
	v_mov_b32_e32 v55, v127
	v_mov_b64_e32 v[62:63], v[122:123]
	v_pk_mul_f32 v[100:101], v[6:7], v[186:187]
	v_pk_mul_f32 v[102:103], v[4:5], v[188:189]
	v_pk_mul_f32 v[104:105], v[10:11], v[190:191]
	v_pk_mul_f32 v[106:107], v[8:9], v[192:193]
	v_pk_mul_f32 v[108:109], v[14:15], v[194:195]
	v_pk_mul_f32 v[110:111], v[12:13], v[214:215]
	v_pk_mul_f32 v[112:113], v[18:19], v[216:217]
	v_pk_mul_f32 v[114:115], v[16:17], v[218:219]
	v_pk_mul_f32 v[116:117], v[22:23], v[220:221]
	v_pk_mul_f32 v[118:119], v[20:21], v[222:223]
	v_pk_mul_f32 v[120:121], v[26:27], v[224:225]
	v_pk_mul_f32 v[122:123], v[24:25], v[226:227]
	v_pk_mul_f32 v[124:125], v[28:29], v[180:181]
	v_pk_mul_f32 v[126:127], v[30:31], v[228:229]
	v_pk_fma_f32 v[66:67], v[176:177], v[96:97], v[66:67]
	v_pk_fma_f32 v[64:65], v[178:179], v[98:99], v[64:65]
	v_pk_fma_f32 v[70:71], v[154:155], v[100:101], v[70:71]
	v_pk_fma_f32 v[68:69], v[152:153], v[102:103], v[68:69]
	v_pk_fma_f32 v[74:75], v[134:135], v[104:105], v[74:75]
	v_pk_fma_f32 v[72:73], v[132:133], v[106:107], v[72:73]
	v_pk_fma_f32 v[78:79], v[130:131], v[108:109], v[78:79]
	v_pk_fma_f32 v[76:77], v[212:213], v[110:111], v[76:77]
	v_pk_fma_f32 v[82:83], v[138:139], v[112:113], v[82:83]
	v_pk_fma_f32 v[80:81], v[136:137], v[114:115], v[80:81]
	v_pk_fma_f32 v[86:87], v[142:143], v[116:117], v[86:87]
	v_pk_fma_f32 v[84:85], v[140:141], v[118:119], v[84:85]
	v_pk_fma_f32 v[90:91], v[146:147], v[120:121], v[90:91]
	v_pk_fma_f32 v[88:89], v[144:145], v[122:123], v[88:89]
	v_pk_fma_f32 v[94:95], v[150:151], v[126:127], v[94:95]
	v_pk_fma_f32 v[92:93], v[148:149], v[124:125], v[92:93]
	v_cvt_pk_bf16_f32 v64, v64, v65
	v_cvt_pk_bf16_f32 v65, v66, v67
	v_cvt_pk_bf16_f32 v66, v68, v69
	v_cvt_pk_bf16_f32 v67, v70, v71
	v_cvt_pk_bf16_f32 v68, v72, v73
	v_cvt_pk_bf16_f32 v69, v74, v75
	v_cvt_pk_bf16_f32 v70, v76, v77
	v_cvt_pk_bf16_f32 v71, v78, v79
	v_cvt_pk_bf16_f32 v72, v80, v81
	v_cvt_pk_bf16_f32 v73, v82, v83
	v_cvt_pk_bf16_f32 v74, v84, v85
	v_cvt_pk_bf16_f32 v75, v86, v87
	v_cvt_pk_bf16_f32 v76, v88, v89
	v_cvt_pk_bf16_f32 v77, v90, v91
	v_cvt_pk_bf16_f32 v78, v92, v93
	v_cvt_pk_bf16_f32 v79, v94, v95
	global_store_dwordx2 v[160:161], v[64:65], off
	global_store_dwordx2 v[160:161], v[66:67], off offset:512
	global_store_dwordx2 v[160:161], v[68:69], off offset:1024
	global_store_dwordx2 v[160:161], v[70:71], off offset:1536
	global_store_dwordx2 v[160:161], v[72:73], off offset:2048
	global_store_dwordx2 v[160:161], v[74:75], off offset:2560
	global_store_dwordx2 v[160:161], v[76:77], off offset:3072
	global_store_dwordx2 v[160:161], v[78:79], off offset:3584
	v_lshl_add_u64 v[160:161], v[160:161], 0, s[4:5]
	s_andn2_b64 exec, exec, s[8:9]
	s_cbranch_execnz .LBB0_129
